# nt cache policy on the weight-conversion streaming loads and stores
# baseline (speedup 1.0000x reference)
.Lcvb_nsl:
	s_lshr_b32 s32, s2, s100
	s_bfm_b32 vcc_lo, s100, 0
	s_and_b32 s2, s2, vcc_lo
	s_lshl_b32 vcc_lo, s11, 8
	s_mul_i32 vcc_lo, vcc_lo, s32
	s_add_u32 s99, s99, vcc_lo
	s_lshl_b32 vcc_lo, s2, 8
	s_add_u32 s99, s99, vcc_lo
	s_lshl_b32 vcc_lo, s12, 7
	s_mul_i32 vcc_lo, vcc_lo, s2
	s_add_u32 s101, s101, vcc_lo
	s_lshl_b32 vcc_lo, s32, 7
	s_add_u32 s101, s101, vcc_lo
	s_cmp_eq_u32 s14, 2
	s_cselect_b32 vcc_lo, s2, s32
	s_lshl_b32 vcc_lo, vcc_lo, 8
	s_add_u32 s13, s13, vcc_lo
	s_waitcnt lgkmcnt(0)
	s_add_u32 s0, s0, s99
	s_addc_u32 s1, s1, 0
	s_add_u32 s4, s4, s101
	s_addc_u32 s5, s5, 0
	s_add_u32 s6, s6, s13
	s_addc_u32 s7, s7, 0
	s_lshl_b32 s10, s11, 4
	s_lshl_b32 s13, s12, 4
	s_lshr_b32 s12, s12, 1
	v_mad_u32_u24 v89, v82, s11, v83
	v_mad_u32_u24 v0, v84, s12, v85
	global_load_dwordx4 v[2:5], v89, s[0:1] nt
	s_add_u32 s0, s0, s10
	s_addc_u32 s1, s1, 0
	global_load_dwordx4 v[6:9], v89, s[0:1] nt
	s_add_u32 s0, s0, s10
	s_addc_u32 s1, s1, 0
	global_load_dwordx4 v[10:13], v89, s[0:1] nt
	s_add_u32 s0, s0, s10
	s_addc_u32 s1, s1, 0
	global_load_dwordx4 v[14:17], v89, s[0:1] nt
	s_add_u32 s0, s0, s10
	s_addc_u32 s1, s1, 0
	global_load_dwordx4 v[18:21], v89, s[0:1] nt
	s_add_u32 s0, s0, s10
	s_addc_u32 s1, s1, 0
	global_load_dwordx4 v[22:25], v89, s[0:1] nt
	s_add_u32 s0, s0, s10
	s_addc_u32 s1, s1, 0
	global_load_dwordx4 v[26:29], v89, s[0:1] nt
	s_add_u32 s0, s0, s10
	s_addc_u32 s1, s1, 0
	global_load_dwordx4 v[30:33], v89, s[0:1] nt
	s_add_u32 s0, s0, s10
	s_addc_u32 s1, s1, 0
	global_load_dwordx4 v[34:37], v89, s[0:1] nt
	s_add_u32 s0, s0, s10
	s_addc_u32 s1, s1, 0
	global_load_dwordx4 v[38:41], v89, s[0:1] nt
	s_add_u32 s0, s0, s10
	s_addc_u32 s1, s1, 0
	global_load_dwordx4 v[42:45], v89, s[0:1] nt
	s_add_u32 s0, s0, s10
	s_addc_u32 s1, s1, 0
	global_load_dwordx4 v[46:49], v89, s[0:1] nt
	s_add_u32 s0, s0, s10
	s_addc_u32 s1, s1, 0
	global_load_dwordx4 v[50:53], v89, s[0:1] nt
	s_add_u32 s0, s0, s10
	s_addc_u32 s1, s1, 0
	global_load_dwordx4 v[54:57], v89, s[0:1] nt
	s_add_u32 s0, s0, s10
	s_addc_u32 s1, s1, 0
	global_load_dwordx4 v[58:61], v89, s[0:1] nt
	s_add_u32 s0, s0, s10
	s_addc_u32 s1, s1, 0
	global_load_dwordx4 v[62:65], v89, s[0:1] nt
	s_cmp_eq_u32 s14, 1
	s_cbranch_scc0 .Lcvb_nrs
	global_load_dword v66, v82, s[6:7] offset:0
	global_load_dword v67, v82, s[6:7] offset:16
	global_load_dword v68, v82, s[6:7] offset:32
	global_load_dword v69, v82, s[6:7] offset:48
	global_load_dword v70, v82, s[6:7] offset:64
	global_load_dword v71, v82, s[6:7] offset:80
	global_load_dword v72, v82, s[6:7] offset:96
	global_load_dword v73, v82, s[6:7] offset:112
	global_load_dword v74, v82, s[6:7] offset:128
	global_load_dword v75, v82, s[6:7] offset:144
	global_load_dword v76, v82, s[6:7] offset:160
	global_load_dword v77, v82, s[6:7] offset:176
	global_load_dword v78, v82, s[6:7] offset:192
	global_load_dword v79, v82, s[6:7] offset:208
	global_load_dword v80, v82, s[6:7] offset:224
	global_load_dword v81, v82, s[6:7] offset:240

.Lcvb_ncm:
	v_cvt_pk_bf16_f32 v2, v2, v3
	v_cvt_pk_bf16_f32 v3, v4, v5
	v_cvt_pk_bf16_f32 v4, v6, v7
	v_cvt_pk_bf16_f32 v5, v8, v9
	global_store_dwordx4 v0, v[2:5], s[4:5] nt
	s_add_u32 s4, s4, s13
	s_addc_u32 s5, s5, 0
	v_cvt_pk_bf16_f32 v10, v10, v11
	v_cvt_pk_bf16_f32 v11, v12, v13
	v_cvt_pk_bf16_f32 v12, v14, v15
	v_cvt_pk_bf16_f32 v13, v16, v17
	global_store_dwordx4 v0, v[10:13], s[4:5] nt
	s_add_u32 s4, s4, s13
	s_addc_u32 s5, s5, 0
	v_cvt_pk_bf16_f32 v18, v18, v19
	v_cvt_pk_bf16_f32 v19, v20, v21
	v_cvt_pk_bf16_f32 v20, v22, v23
	v_cvt_pk_bf16_f32 v21, v24, v25
	global_store_dwordx4 v0, v[18:21], s[4:5] nt
	s_add_u32 s4, s4, s13
	s_addc_u32 s5, s5, 0
	v_cvt_pk_bf16_f32 v26, v26, v27
	v_cvt_pk_bf16_f32 v27, v28, v29
	v_cvt_pk_bf16_f32 v28, v30, v31
	v_cvt_pk_bf16_f32 v29, v32, v33
	global_store_dwordx4 v0, v[26:29], s[4:5] nt
	s_add_u32 s4, s4, s13
	s_addc_u32 s5, s5, 0
	v_cvt_pk_bf16_f32 v34, v34, v35
	v_cvt_pk_bf16_f32 v35, v36, v37
	v_cvt_pk_bf16_f32 v36, v38, v39
	v_cvt_pk_bf16_f32 v37, v40, v41
	global_store_dwordx4 v0, v[34:37], s[4:5] nt
	s_add_u32 s4, s4, s13
	s_addc_u32 s5, s5, 0
	v_cvt_pk_bf16_f32 v42, v42, v43
	v_cvt_pk_bf16_f32 v43, v44, v45
	v_cvt_pk_bf16_f32 v44, v46, v47
	v_cvt_pk_bf16_f32 v45, v48, v49
	global_store_dwordx4 v0, v[42:45], s[4:5] nt
	s_add_u32 s4, s4, s13
	s_addc_u32 s5, s5, 0
	v_cvt_pk_bf16_f32 v50, v50, v51
	v_cvt_pk_bf16_f32 v51, v52, v53
	v_cvt_pk_bf16_f32 v52, v54, v55
	v_cvt_pk_bf16_f32 v53, v56, v57
	global_store_dwordx4 v0, v[50:53], s[4:5] nt
	s_add_u32 s4, s4, s13
	s_addc_u32 s5, s5, 0
	v_cvt_pk_bf16_f32 v58, v58, v59
	v_cvt_pk_bf16_f32 v59, v60, v61
	v_cvt_pk_bf16_f32 v60, v62, v63
	v_cvt_pk_bf16_f32 v61, v64, v65
	global_store_dwordx4 v0, v[58:61], s[4:5] nt

.Lcva_nsl:
	s_lshr_b32 s32, s2, s100
	s_bfm_b32 vcc_lo, s100, 0
	s_and_b32 s2, s2, vcc_lo
	s_lshl_b32 vcc_lo, s11, 8
	s_mul_i32 vcc_lo, vcc_lo, s32
	s_add_u32 s99, s99, vcc_lo
	s_lshl_b32 vcc_lo, s2, 8
	s_add_u32 s99, s99, vcc_lo
	s_lshl_b32 vcc_lo, s12, 7
	s_mul_i32 vcc_lo, vcc_lo, s2
	s_add_u32 s101, s101, vcc_lo
	s_lshl_b32 vcc_lo, s32, 7
	s_add_u32 s101, s101, vcc_lo
	s_cmp_eq_u32 s14, 2
	s_cselect_b32 vcc_lo, s2, s32
	s_lshl_b32 vcc_lo, vcc_lo, 8
	s_add_u32 s13, s13, vcc_lo
	s_waitcnt lgkmcnt(0)
	s_add_u32 s0, s0, s99
	s_addc_u32 s1, s1, 0
	s_add_u32 s4, s4, s101
	s_addc_u32 s5, s5, 0
	s_add_u32 s6, s6, s13
	s_addc_u32 s7, s7, 0
	s_lshl_b32 s10, s11, 4
	s_lshl_b32 s13, s12, 4
	s_lshr_b32 s12, s12, 1
	v_mad_u32_u24 v90, v83, s11, v84
	v_mad_u32_u24 v91, v85, s12, v86
	global_load_dwordx4 v[2:5], v90, s[0:1] nt
	s_add_u32 s0, s0, s10
	s_addc_u32 s1, s1, 0
	global_load_dwordx4 v[6:9], v90, s[0:1] nt
	s_add_u32 s0, s0, s10
	s_addc_u32 s1, s1, 0
	global_load_dwordx4 v[10:13], v90, s[0:1] nt
	s_add_u32 s0, s0, s10
	s_addc_u32 s1, s1, 0
	global_load_dwordx4 v[14:17], v90, s[0:1] nt
	s_add_u32 s0, s0, s10
	s_addc_u32 s1, s1, 0
	global_load_dwordx4 v[18:21], v90, s[0:1] nt
	s_add_u32 s0, s0, s10
	s_addc_u32 s1, s1, 0
	global_load_dwordx4 v[22:25], v90, s[0:1] nt
	s_add_u32 s0, s0, s10
	s_addc_u32 s1, s1, 0
	global_load_dwordx4 v[26:29], v90, s[0:1] nt
	s_add_u32 s0, s0, s10
	s_addc_u32 s1, s1, 0
	global_load_dwordx4 v[30:33], v90, s[0:1] nt
	s_add_u32 s0, s0, s10
	s_addc_u32 s1, s1, 0
	global_load_dwordx4 v[34:37], v90, s[0:1] nt
	s_add_u32 s0, s0, s10
	s_addc_u32 s1, s1, 0
	global_load_dwordx4 v[38:41], v90, s[0:1] nt
	s_add_u32 s0, s0, s10
	s_addc_u32 s1, s1, 0
	global_load_dwordx4 v[42:45], v90, s[0:1] nt
	s_add_u32 s0, s0, s10
	s_addc_u32 s1, s1, 0
	global_load_dwordx4 v[46:49], v90, s[0:1] nt
	s_add_u32 s0, s0, s10
	s_addc_u32 s1, s1, 0
	global_load_dwordx4 v[50:53], v90, s[0:1] nt
	s_add_u32 s0, s0, s10
	s_addc_u32 s1, s1, 0
	global_load_dwordx4 v[54:57], v90, s[0:1] nt
	s_add_u32 s0, s0, s10
	s_addc_u32 s1, s1, 0
	global_load_dwordx4 v[58:61], v90, s[0:1] nt
	s_add_u32 s0, s0, s10
	s_addc_u32 s1, s1, 0
	global_load_dwordx4 v[62:65], v90, s[0:1] nt
	s_cmp_eq_u32 s14, 1
	s_cbranch_scc0 .Lcva_nrs
	global_load_dword v66, v83, s[6:7] offset:0
	global_load_dword v67, v83, s[6:7] offset:16
	global_load_dword v68, v83, s[6:7] offset:32
	global_load_dword v69, v83, s[6:7] offset:48
	global_load_dword v70, v83, s[6:7] offset:64
	global_load_dword v71, v83, s[6:7] offset:80
	global_load_dword v72, v83, s[6:7] offset:96
	global_load_dword v74, v83, s[6:7] offset:112
	global_load_dword v75, v83, s[6:7] offset:128
	global_load_dword v76, v83, s[6:7] offset:144
	global_load_dword v77, v83, s[6:7] offset:160
	global_load_dword v78, v83, s[6:7] offset:176
	global_load_dword v79, v83, s[6:7] offset:192
	global_load_dword v80, v83, s[6:7] offset:208
	global_load_dword v81, v83, s[6:7] offset:224
	global_load_dword v82, v83, s[6:7] offset:240

.Lcva_ncm:
	v_cvt_pk_bf16_f32 v2, v2, v3
	v_cvt_pk_bf16_f32 v3, v4, v5
	v_cvt_pk_bf16_f32 v4, v6, v7
	v_cvt_pk_bf16_f32 v5, v8, v9
	global_store_dwordx4 v91, v[2:5], s[4:5] nt
	s_add_u32 s4, s4, s13
	s_addc_u32 s5, s5, 0
	v_cvt_pk_bf16_f32 v10, v10, v11
	v_cvt_pk_bf16_f32 v11, v12, v13
	v_cvt_pk_bf16_f32 v12, v14, v15
	v_cvt_pk_bf16_f32 v13, v16, v17
	global_store_dwordx4 v91, v[10:13], s[4:5] nt
	s_add_u32 s4, s4, s13
	s_addc_u32 s5, s5, 0
	v_cvt_pk_bf16_f32 v18, v18, v19
	v_cvt_pk_bf16_f32 v19, v20, v21
	v_cvt_pk_bf16_f32 v20, v22, v23
	v_cvt_pk_bf16_f32 v21, v24, v25
	global_store_dwordx4 v91, v[18:21], s[4:5] nt
	s_add_u32 s4, s4, s13
	s_addc_u32 s5, s5, 0
	v_cvt_pk_bf16_f32 v26, v26, v27
	v_cvt_pk_bf16_f32 v27, v28, v29
	v_cvt_pk_bf16_f32 v28, v30, v31
	v_cvt_pk_bf16_f32 v29, v32, v33
	global_store_dwordx4 v91, v[26:29], s[4:5] nt
	s_add_u32 s4, s4, s13
	s_addc_u32 s5, s5, 0
	v_cvt_pk_bf16_f32 v34, v34, v35
	v_cvt_pk_bf16_f32 v35, v36, v37
	v_cvt_pk_bf16_f32 v36, v38, v39
	v_cvt_pk_bf16_f32 v37, v40, v41
	global_store_dwordx4 v91, v[34:37], s[4:5] nt
	s_add_u32 s4, s4, s13
	s_addc_u32 s5, s5, 0
	v_cvt_pk_bf16_f32 v42, v42, v43
	v_cvt_pk_bf16_f32 v43, v44, v45
	v_cvt_pk_bf16_f32 v44, v46, v47
	v_cvt_pk_bf16_f32 v45, v48, v49
	global_store_dwordx4 v91, v[42:45], s[4:5] nt
	s_add_u32 s4, s4, s13
	s_addc_u32 s5, s5, 0
	v_cvt_pk_bf16_f32 v50, v50, v51
	v_cvt_pk_bf16_f32 v51, v52, v53
	v_cvt_pk_bf16_f32 v52, v54, v55
	v_cvt_pk_bf16_f32 v53, v56, v57
	global_store_dwordx4 v91, v[50:53], s[4:5] nt
	s_add_u32 s4, s4, s13
	s_addc_u32 s5, s5, 0
	v_cvt_pk_bf16_f32 v58, v58, v59
	v_cvt_pk_bf16_f32 v59, v60, v61
	v_cvt_pk_bf16_f32 v60, v62, v63
	v_cvt_pk_bf16_f32 v61, v64, v65
	global_store_dwordx4 v91, v[58:61], s[4:5] nt
